# lever 7.3: FoX and NSA unit outputs written as 4 x dwordx4 per lane after exchanging 8-byte halves with v_permlane32_swap (were 8 x dwordx2)
# speedup vs baseline: 1.0091x; 1.0026x over previous
.LBB0_746:
	v_div_scale_f32 v0, s[0:1], v86, v86, 1.0
	v_rcp_f32_e32 v2, v0
	v_ashrrev_i32_e32 v153, 31, v152
	v_mov_b32_e32 v159, v1
	s_xor_b64 s[0:1], s[2:3], -1
	v_fma_f32 v3, -v0, v2, 1.0
	v_fmac_f32_e32 v2, v3, v2
	v_div_scale_f32 v3, vcc, 1.0, v86, 1.0
	v_mul_f32_e32 v4, v3, v2
	v_fma_f32 v5, -v0, v4, v3
	v_fmac_f32_e32 v4, v5, v2
	v_fma_f32 v0, -v0, v4, v3
	v_div_fmas_f32 v0, v0, v2, v4
	v_div_fixup_f32 v0, v0, v86, 1.0
	v_cmp_lt_f32_e32 vcc, 0, v86
	s_mov_b64 s[2:3], 0xbe00000
	s_nop 0
	v_cndmask_b32_e32 v0, 0, v0, vcc
	v_mul_f32_e32 v20, v20, v0
	v_mul_f32_e32 v21, v21, v0
	v_mul_f32_e32 v22, v22, v0
	v_mul_f32_e32 v23, v23, v0
	v_mul_f32_e32 v24, v24, v0
	v_mul_f32_e32 v25, v25, v0
	v_mul_f32_e32 v26, v26, v0
	v_mul_f32_e32 v27, v27, v0
	v_mul_f32_e32 v28, v28, v0
	v_mul_f32_e32 v29, v29, v0
	v_mul_f32_e32 v30, v30, v0
	v_mul_f32_e32 v31, v31, v0
	v_mul_f32_e32 v32, v32, v0
	v_mul_f32_e32 v33, v33, v0
	v_mul_f32_e32 v34, v34, v0
	v_mul_f32_e32 v35, v35, v0
	v_mul_f32_e32 v36, v36, v0
	v_mul_f32_e32 v37, v37, v0
	v_mul_f32_e32 v38, v38, v0
	v_mul_f32_e32 v39, v39, v0
	v_mul_f32_e32 v40, v40, v0
	v_mul_f32_e32 v41, v41, v0
	v_mul_f32_e32 v42, v42, v0
	v_mul_f32_e32 v43, v43, v0
	v_mul_f32_e32 v44, v44, v0
	v_mul_f32_e32 v45, v45, v0
	v_mul_f32_e32 v46, v46, v0
	v_mul_f32_e32 v47, v47, v0
	v_mul_f32_e32 v48, v48, v0
	v_mul_f32_e32 v49, v49, v0
	v_mul_f32_e32 v50, v50, v0
	v_mul_f32_e32 v51, v51, v0
	v_cvt_pk_bf16_f32 v2, v36, v37
	v_cvt_pk_bf16_f32 v3, v38, v39
	v_cvt_pk_bf16_f32 v4, v44, v45
	v_cvt_pk_bf16_f32 v5, v46, v47
	v_cvt_pk_bf16_f32 v6, v40, v41
	v_cvt_pk_bf16_f32 v7, v42, v43
	v_cvt_pk_bf16_f32 v8, v48, v49
	v_cvt_pk_bf16_f32 v9, v50, v51
	v_cvt_pk_bf16_f32 v10, v20, v21
	v_cvt_pk_bf16_f32 v11, v22, v23
	v_cvt_pk_bf16_f32 v12, v28, v29
	v_cvt_pk_bf16_f32 v13, v30, v31
	v_cvt_pk_bf16_f32 v14, v24, v25
	v_cvt_pk_bf16_f32 v15, v26, v27
	v_cvt_pk_bf16_f32 v16, v32, v33
	v_cvt_pk_bf16_f32 v17, v34, v35
	v_lshlrev_b64 v[18:19], 11, v[152:153]
	v_lshl_add_u64 v[18:19], s[30:31], 0, v[18:19]
	v_lshl_add_u64 v[18:19], v[18:19], 0, s[80:81]
	v_lshl_add_u64 v[18:19], v[158:159], 3, v[18:19]
	s_mov_b64 s[2:3], 0xbe00000
	v_lshl_add_u64 v[18:19], v[18:19], 0, s[2:3]
	s_nop 1
	v_permlane32_swap_b32_e32 v2, v4
	v_permlane32_swap_b32_e32 v3, v5
	v_permlane32_swap_b32_e32 v6, v8
	v_permlane32_swap_b32_e32 v7, v9
	v_permlane32_swap_b32_e32 v10, v12
	v_permlane32_swap_b32_e32 v11, v13
	v_permlane32_swap_b32_e32 v14, v16
	v_permlane32_swap_b32_e32 v15, v17
	s_mov_b64 s[2:3], 0
	s_and_b64 vcc, exec, s[0:1]
	global_store_dwordx4 v[18:19], v[2:5], off
	global_store_dwordx4 v[18:19], v[6:9], off offset:16
	global_store_dwordx4 v[18:19], v[10:13], off offset:64
	global_store_dwordx4 v[18:19], v[14:17], off offset:80
	s_cbranch_vccnz .LBB0_822

.LBB0_823:
	s_or_b64 exec, exec, s[0:1]
	ds_read_b128 v[2:5], v215 offset:56064
	ds_read_b128 v[6:9], v178 offset:32768
	ds_read_b128 v[10:13], v215 offset:64256
	ds_read_b128 v[32:35], v178 offset:16384
	v_readlane_b32 s0, v254, 51
	s_waitcnt lgkmcnt(3)
	v_pk_fma_f32 v[36:37], v[16:17], v[0:1], v[2:3] op_sel_hi:[1,0,1]
	v_pk_fma_f32 v[18:19], v[18:19], v[0:1], v[4:5] op_sel_hi:[1,0,1]
	ds_read_b128 v[2:5], v178 offset:24576
	s_waitcnt lgkmcnt(3)
	v_pk_fma_f32 v[38:39], v[48:49], v[0:1], v[6:7] op_sel_hi:[1,0,1]
	ds_read_b128 v[14:17], v214
	v_pk_fma_f32 v[40:41], v[50:51], v[0:1], v[8:9] op_sel_hi:[1,0,1]
	s_waitcnt lgkmcnt(3)
	v_pk_fma_f32 v[20:21], v[20:21], v[0:1], v[10:11] op_sel_hi:[1,0,1]
	ds_read_b128 v[6:9], v213
	v_pk_fma_f32 v[22:23], v[22:23], v[0:1], v[12:13] op_sel_hi:[1,0,1]
	ds_read_b128 v[10:13], v179
	s_waitcnt lgkmcnt(3)
	v_pk_fma_f32 v[2:3], v[28:29], v[0:1], v[2:3] op_sel_hi:[1,0,1]
	v_lshlrev_b64 v[28:29], 11, v[166:167]
	v_readlane_b32 s1, v254, 52
	s_waitcnt lgkmcnt(2)
	v_pk_fma_f32 v[14:15], v[52:53], v[0:1], v[14:15] op_sel_hi:[1,0,1]
	v_pk_fma_f32 v[16:17], v[54:55], v[0:1], v[16:17] op_sel_hi:[1,0,1]
	v_pk_fma_f32 v[24:25], v[24:25], v[0:1], v[32:33] op_sel_hi:[1,0,1]
	s_waitcnt lgkmcnt(1)
	v_pk_fma_f32 v[6:7], v[56:57], v[0:1], v[6:7] op_sel_hi:[1,0,1]
	v_pk_fma_f32 v[26:27], v[26:27], v[0:1], v[34:35] op_sel_hi:[1,0,1]
	v_pk_fma_f32 v[8:9], v[58:59], v[0:1], v[8:9] op_sel_hi:[1,0,1]
	s_waitcnt lgkmcnt(0)
	v_pk_fma_f32 v[10:11], v[60:61], v[0:1], v[10:11] op_sel_hi:[1,0,1]
	v_pk_fma_f32 v[4:5], v[30:31], v[0:1], v[4:5] op_sel_hi:[1,0,1]
	v_pk_fma_f32 v[12:13], v[62:63], v[0:1], v[12:13] op_sel_hi:[1,0,1]
	v_lshl_add_u64 v[28:29], s[0:1], 0, v[28:29]
	v_lshlrev_b32_e32 v0, 1, v169
	v_lshl_add_u64 v[28:29], v[28:29], 0, v[0:1]
	v_lshlrev_b32_e32 v0, 5, v204
	v_lshl_add_u64 v[28:29], v[28:29], 0, v[0:1]
	s_mov_b64 s[0:1], 0xbe00400
	v_lshl_add_u64 v[30:31], v[28:29], 0, s[0:1]
	v_cvt_pk_bf16_f32 v48, v36, v37
	v_cvt_pk_bf16_f32 v49, v18, v19
	v_cvt_pk_bf16_f32 v50, v24, v25
	v_cvt_pk_bf16_f32 v51, v26, v27
	v_cvt_pk_bf16_f32 v52, v20, v21
	v_cvt_pk_bf16_f32 v53, v22, v23
	v_cvt_pk_bf16_f32 v54, v2, v3
	v_cvt_pk_bf16_f32 v55, v4, v5
	v_cvt_pk_bf16_f32 v56, v38, v39
	v_cvt_pk_bf16_f32 v57, v40, v41
	v_cvt_pk_bf16_f32 v58, v6, v7
	v_cvt_pk_bf16_f32 v59, v8, v9
	v_cvt_pk_bf16_f32 v60, v14, v15
	v_cvt_pk_bf16_f32 v61, v16, v17
	v_cvt_pk_bf16_f32 v62, v10, v11
	v_cvt_pk_bf16_f32 v63, v12, v13
	v_readlane_b32 s2, v254, 56
	v_readlane_b32 s3, v254, 57
	s_mov_b64 s[0:1], 0
	s_nop 0
	v_permlane32_swap_b32_e32 v48, v50
	v_permlane32_swap_b32_e32 v49, v51
	v_permlane32_swap_b32_e32 v52, v54
	v_permlane32_swap_b32_e32 v53, v55
	v_permlane32_swap_b32_e32 v56, v58
	v_permlane32_swap_b32_e32 v57, v59
	v_permlane32_swap_b32_e32 v60, v62
	v_permlane32_swap_b32_e32 v61, v63
	s_and_b64 vcc, exec, s[2:3]
	global_store_dwordx4 v[30:31], v[48:51], off
	global_store_dwordx4 v[30:31], v[52:55], off offset:16
	global_store_dwordx4 v[30:31], v[56:59], off offset:64
	global_store_dwordx4 v[30:31], v[60:63], off offset:80
	s_barrier
	s_cbranch_vccnz .LBB0_744
